# P3 epilogue: all 16 x loads + bias of a half issued up front (was 16 dependent HBM round trips)
# speedup vs baseline: 1.0011x; 1.0011x over previous
; DI unsigned pack2(float a, float b) { const f32x2 v = {a, b}; const bf16x2_t r = __builtin_convertvector(v, bf16x2_t); return __builtin_bit_cast(unsigned, r); }
; DI void outproj_epilogue(const Params& p, const char* smem, const int m0, const int n0) {
;   u16* rbuf = (u16*)(p.ws + WS_PU);
;   const float* ct = (const float*)smem;
; #pragma unroll 4
;   for (int i = 0; i < 16; ++i) {
;     const int c = threadIdx.x + NT * i, row = c >> 5, ch = c & 31;
;     const float4 y = *(const float4*)(ct + row * CT_PITCH + 4 * ch);
;     const size_t o = (size_t)(m0 + row) * 1024 + n0 + 4 * ch;
;     const float4 xv = *(const float4*)(p.x + o), bv = *(const float4*)(p.b_out + n0 + 4 * ch);
;     uint2 r; r.x = pack2(ALPHA * xv.x + y.x + bv.x, ALPHA * xv.y + y.y + bv.y); r.y = pack2(ALPHA * xv.z + y.z + bv.z, ALPHA * xv.w + y.w + bv.w);
;     *(uint2*)(rbuf + o) = r;
;   }
; }
.LBB0_294:
	s_ashr_i32 s27, s26, 31
	v_mov_b32_e32 v141, s27
	v_or_b32_e32 v140, s26, v130
	v_lshl_add_u64 v[138:139], s[26:27], 2, v[136:137]
	v_add_u32_e32 v162, s0, v149
	v_add_u32_e32 v163, s0, v151
	v_add_u32_e32 v164, s0, v153
	s_mov_b32 s0, 0
	v_mov_b32_e32 v165, v154
	v_mov_b32_e32 v166, v152
	v_mov_b32_e32 v167, v150
	v_lshl_add_u32 v180, v164, 10, v140
	v_lshl_add_u32 v181, v163, 10, v140
	v_lshl_add_u32 v183, v162, 10, v140
	v_add_u32_e32 v182, 0x8000, v180
	v_lshlrev_b32_e32 v168, 2, v180
	v_lshlrev_b32_e32 v169, 2, v181
	v_lshlrev_b32_e32 v170, 2, v182
	v_lshlrev_b32_e32 v171, 2, v183
	v_lshl_add_u32 v180, v164, 10, v140
	v_lshl_add_u32 v181, v163, 10, v140
	v_lshl_add_u32 v183, v162, 10, v140
	v_add_u32_e32 v182, 0x8000, v180
	v_lshlrev_b32_e32 v172, 1, v180
	v_lshlrev_b32_e32 v173, 1, v181
	v_lshlrev_b32_e32 v174, 1, v182
	v_lshlrev_b32_e32 v175, 1, v183
	global_load_dwordx4 v[176:179], v[138:139], off
	s_mov_b64 s[98:99], s[52:53]
	global_load_dwordx4 v[188:191], v168, s[98:99]
	global_load_dwordx4 v[192:195], v169, s[98:99]
	global_load_dwordx4 v[196:199], v170, s[98:99]
	global_load_dwordx4 v[202:205], v171, s[98:99]
	s_add_u32 s98, s98, 0x40000
	s_addc_u32 s99, s99, 0
	global_load_dwordx4 v[206:209], v168, s[98:99]
	global_load_dwordx4 v[210:213], v169, s[98:99]
	global_load_dwordx4 v[214:217], v170, s[98:99]
	global_load_dwordx4 v[218:221], v171, s[98:99]
	s_add_u32 s98, s98, 0x40000
	s_addc_u32 s99, s99, 0
	global_load_dwordx4 v[222:225], v168, s[98:99]
	global_load_dwordx4 v[226:229], v169, s[98:99]
	global_load_dwordx4 v[230:233], v170, s[98:99]
	global_load_dwordx4 v[234:237], v171, s[98:99]
	s_add_u32 s98, s98, 0x40000
	s_addc_u32 s99, s99, 0
	global_load_dwordx4 v[240:243], v168, s[98:99]
	global_load_dwordx4 v[244:247], v169, s[98:99]
	global_load_dwordx4 v[248:251], v170, s[98:99]
	global_load_dwordx4 v[252:255], v171, s[98:99]
	s_waitcnt lgkmcnt(0)
	s_barrier
	s_mov_b64 s[98:99], s[14:15]
	ds_read_b128 v[180:183], v165
	ds_read_b128 v[184:187], v166
	s_waitcnt vmcnt(15) lgkmcnt(1)
	v_pk_fma_f32 v[188:189], v[188:189], s[24:25], v[180:181] op_sel_hi:[1,0,1]
	v_pk_fma_f32 v[190:191], v[190:191], s[24:25], v[182:183] op_sel_hi:[1,0,1]
	ds_read_b128 v[180:183], v165 offset:16896
	v_pk_add_f32 v[188:189], v[188:189], v[176:177]
	v_pk_add_f32 v[190:191], v[190:191], v[178:179]
	v_cvt_pk_bf16_f32 v188, v188, v189
	v_cvt_pk_bf16_f32 v189, v190, v191
	global_store_dwordx2 v172, v[188:189], s[98:99]
	s_waitcnt vmcnt(15) lgkmcnt(1)
	v_pk_fma_f32 v[192:193], v[192:193], s[24:25], v[184:185] op_sel_hi:[1,0,1]
	v_pk_fma_f32 v[194:195], v[194:195], s[24:25], v[186:187] op_sel_hi:[1,0,1]
	ds_read_b128 v[184:187], v167
	v_pk_add_f32 v[192:193], v[192:193], v[176:177]
	v_pk_add_f32 v[194:195], v[194:195], v[178:179]
	v_cvt_pk_bf16_f32 v192, v192, v193
	v_cvt_pk_bf16_f32 v193, v194, v195
	global_store_dwordx2 v173, v[192:193], s[98:99]
	s_waitcnt vmcnt(15) lgkmcnt(1)
	v_pk_fma_f32 v[196:197], v[196:197], s[24:25], v[180:181] op_sel_hi:[1,0,1]
	v_pk_fma_f32 v[198:199], v[198:199], s[24:25], v[182:183] op_sel_hi:[1,0,1]
	v_pk_add_f32 v[196:197], v[196:197], v[176:177]
	v_pk_add_f32 v[198:199], v[198:199], v[178:179]
	v_cvt_pk_bf16_f32 v196, v196, v197
	v_cvt_pk_bf16_f32 v197, v198, v199
	global_store_dwordx2 v174, v[196:197], s[98:99]
	s_waitcnt vmcnt(15) lgkmcnt(0)
	v_pk_fma_f32 v[202:203], v[202:203], s[24:25], v[184:185] op_sel_hi:[1,0,1]
	v_pk_fma_f32 v[204:205], v[204:205], s[24:25], v[186:187] op_sel_hi:[1,0,1]
	v_pk_add_f32 v[202:203], v[202:203], v[176:177]
	v_pk_add_f32 v[204:205], v[204:205], v[178:179]
	v_cvt_pk_bf16_f32 v202, v202, v203
	v_cvt_pk_bf16_f32 v203, v204, v205
	global_store_dwordx2 v175, v[202:203], s[98:99]
	v_add_u32_e32 v165, 0x8400, v165
	v_add_u32_e32 v166, 0x8400, v166
	v_add_u32_e32 v167, 0x8400, v167
	s_add_u32 s98, s98, 0x20000
	s_addc_u32 s99, s99, 0
	ds_read_b128 v[180:183], v165
	ds_read_b128 v[184:187], v166
	s_waitcnt vmcnt(15) lgkmcnt(1)
	v_pk_fma_f32 v[206:207], v[206:207], s[24:25], v[180:181] op_sel_hi:[1,0,1]
	v_pk_fma_f32 v[208:209], v[208:209], s[24:25], v[182:183] op_sel_hi:[1,0,1]
	ds_read_b128 v[180:183], v165 offset:16896
	v_pk_add_f32 v[206:207], v[206:207], v[176:177]
	v_pk_add_f32 v[208:209], v[208:209], v[178:179]
	v_cvt_pk_bf16_f32 v206, v206, v207
	v_cvt_pk_bf16_f32 v207, v208, v209
	global_store_dwordx2 v172, v[206:207], s[98:99]
	s_waitcnt vmcnt(15) lgkmcnt(1)
	v_pk_fma_f32 v[210:211], v[210:211], s[24:25], v[184:185] op_sel_hi:[1,0,1]
	v_pk_fma_f32 v[212:213], v[212:213], s[24:25], v[186:187] op_sel_hi:[1,0,1]
	ds_read_b128 v[184:187], v167
	v_pk_add_f32 v[210:211], v[210:211], v[176:177]
	v_pk_add_f32 v[212:213], v[212:213], v[178:179]
	v_cvt_pk_bf16_f32 v210, v210, v211
	v_cvt_pk_bf16_f32 v211, v212, v213
	global_store_dwordx2 v173, v[210:211], s[98:99]
	s_waitcnt vmcnt(15) lgkmcnt(1)
	v_pk_fma_f32 v[214:215], v[214:215], s[24:25], v[180:181] op_sel_hi:[1,0,1]
	v_pk_fma_f32 v[216:217], v[216:217], s[24:25], v[182:183] op_sel_hi:[1,0,1]
	v_pk_add_f32 v[214:215], v[214:215], v[176:177]
	v_pk_add_f32 v[216:217], v[216:217], v[178:179]
	v_cvt_pk_bf16_f32 v214, v214, v215
	v_cvt_pk_bf16_f32 v215, v216, v217
	global_store_dwordx2 v174, v[214:215], s[98:99]
	s_waitcnt vmcnt(15) lgkmcnt(0)
	v_pk_fma_f32 v[218:219], v[218:219], s[24:25], v[184:185] op_sel_hi:[1,0,1]
	v_pk_fma_f32 v[220:221], v[220:221], s[24:25], v[186:187] op_sel_hi:[1,0,1]
	v_pk_add_f32 v[218:219], v[218:219], v[176:177]
	v_pk_add_f32 v[220:221], v[220:221], v[178:179]
	v_cvt_pk_bf16_f32 v218, v218, v219
	v_cvt_pk_bf16_f32 v219, v220, v221
	global_store_dwordx2 v175, v[218:219], s[98:99]
	v_add_u32_e32 v165, 0x8400, v165
	v_add_u32_e32 v166, 0x8400, v166
	v_add_u32_e32 v167, 0x8400, v167
	s_add_u32 s98, s98, 0x20000
	s_addc_u32 s99, s99, 0
	ds_read_b128 v[180:183], v165
	ds_read_b128 v[184:187], v166
	s_waitcnt vmcnt(15) lgkmcnt(1)
; DI unsigned pack2(float a, float b) { const f32x2 v = {a, b}; const bf16x2_t r = __builtin_convertvector(v, bf16x2_t); return __builtin_bit_cast(unsigned, r); }
; template <int HF>
; DI void stage_acc_big(const f32x4 (&acc)[8][4], char* smem, const int g, const int r16) {
;   const int w = __builtin_amdgcn_readfirstlane(threadIdx.x >> 6), wm = w & 1, wn = w >> 1;
;   if ((wn >> 1) != HF) return;
;   float* ct = (float*)smem;
; #pragma unroll
;   for (int mi = 0; mi < 8; ++mi)
; #pragma unroll
;     for (int ni = 0; ni < 4; ++ni)
; #pragma unroll
;       for (int j = 0; j < 4; ++j) ct[(128 * wm + 16 * mi + 4 * g + j) * CT_PITCH + 64 * (wn & 1) + 16 * ni + r16] = acc[mi][ni][j];
; }
; DI void outproj_epilogue(const Params& p, const char* smem, const int m0, const int n0) {
;     ...
; #pragma unroll 4
;   for (int i = 0; i < 16; ++i) {
;     const int c = threadIdx.x + NT * i, row = c >> 5, ch = c & 31;
;     const float4 y = *(const float4*)(ct + row * CT_PITCH + 4 * ch);
;     const size_t o = (size_t)(m0 + row) * 1024 + n0 + 4 * ch;
;     const float4 xv = *(const float4*)(p.x + o), bv = *(const float4*)(p.b_out + n0 + 4 * ch);
;     uint2 r; r.x = pack2(ALPHA * xv.x + y.x + bv.x, ALPHA * xv.y + y.y + bv.y); r.y = pack2(ALPHA * xv.z + y.z + bv.z, ALPHA * xv.w + y.w + bv.w);
;     *(uint2*)(rbuf + o) = r;
;   }
	v_pk_fma_f32 v[222:223], v[222:223], s[24:25], v[180:181] op_sel_hi:[1,0,1]
	v_pk_fma_f32 v[224:225], v[224:225], s[24:25], v[182:183] op_sel_hi:[1,0,1]
	ds_read_b128 v[180:183], v165 offset:16896
	v_pk_add_f32 v[222:223], v[222:223], v[176:177]
	v_pk_add_f32 v[224:225], v[224:225], v[178:179]
	v_cvt_pk_bf16_f32 v222, v222, v223
	v_cvt_pk_bf16_f32 v223, v224, v225
	global_store_dwordx2 v172, v[222:223], s[98:99]
	s_waitcnt vmcnt(15) lgkmcnt(1)
	v_pk_fma_f32 v[226:227], v[226:227], s[24:25], v[184:185] op_sel_hi:[1,0,1]
	v_pk_fma_f32 v[228:229], v[228:229], s[24:25], v[186:187] op_sel_hi:[1,0,1]
	ds_read_b128 v[184:187], v167
	v_pk_add_f32 v[226:227], v[226:227], v[176:177]
	v_pk_add_f32 v[228:229], v[228:229], v[178:179]
	v_cvt_pk_bf16_f32 v226, v226, v227
	v_cvt_pk_bf16_f32 v227, v228, v229
	global_store_dwordx2 v173, v[226:227], s[98:99]
	s_waitcnt vmcnt(15) lgkmcnt(1)
	v_pk_fma_f32 v[230:231], v[230:231], s[24:25], v[180:181] op_sel_hi:[1,0,1]
	v_pk_fma_f32 v[232:233], v[232:233], s[24:25], v[182:183] op_sel_hi:[1,0,1]
	v_pk_add_f32 v[230:231], v[230:231], v[176:177]
	v_pk_add_f32 v[232:233], v[232:233], v[178:179]
	v_cvt_pk_bf16_f32 v230, v230, v231
	v_cvt_pk_bf16_f32 v231, v232, v233
	global_store_dwordx2 v174, v[230:231], s[98:99]
	s_waitcnt vmcnt(15) lgkmcnt(0)
	v_pk_fma_f32 v[234:235], v[234:235], s[24:25], v[184:185] op_sel_hi:[1,0,1]
	v_pk_fma_f32 v[236:237], v[236:237], s[24:25], v[186:187] op_sel_hi:[1,0,1]
	v_pk_add_f32 v[234:235], v[234:235], v[176:177]
	v_pk_add_f32 v[236:237], v[236:237], v[178:179]
	v_cvt_pk_bf16_f32 v234, v234, v235
	v_cvt_pk_bf16_f32 v235, v236, v237
	global_store_dwordx2 v175, v[234:235], s[98:99]
	v_add_u32_e32 v165, 0x8400, v165
	v_add_u32_e32 v166, 0x8400, v166
	v_add_u32_e32 v167, 0x8400, v167
	s_add_u32 s98, s98, 0x20000
	s_addc_u32 s99, s99, 0
	ds_read_b128 v[180:183], v165
	ds_read_b128 v[184:187], v166
	s_waitcnt vmcnt(15) lgkmcnt(1)
	v_pk_fma_f32 v[240:241], v[240:241], s[24:25], v[180:181] op_sel_hi:[1,0,1]
	v_pk_fma_f32 v[242:243], v[242:243], s[24:25], v[182:183] op_sel_hi:[1,0,1]
	ds_read_b128 v[180:183], v165 offset:16896
	v_pk_add_f32 v[240:241], v[240:241], v[176:177]
	v_pk_add_f32 v[242:243], v[242:243], v[178:179]
	v_cvt_pk_bf16_f32 v240, v240, v241
	v_cvt_pk_bf16_f32 v241, v242, v243
	global_store_dwordx2 v172, v[240:241], s[98:99]
	s_waitcnt vmcnt(15) lgkmcnt(1)
	v_pk_fma_f32 v[244:245], v[244:245], s[24:25], v[184:185] op_sel_hi:[1,0,1]
	v_pk_fma_f32 v[246:247], v[246:247], s[24:25], v[186:187] op_sel_hi:[1,0,1]
	ds_read_b128 v[184:187], v167
	v_pk_add_f32 v[244:245], v[244:245], v[176:177]
	v_pk_add_f32 v[246:247], v[246:247], v[178:179]
	v_cvt_pk_bf16_f32 v244, v244, v245
	v_cvt_pk_bf16_f32 v245, v246, v247
	global_store_dwordx2 v173, v[244:245], s[98:99]
	s_waitcnt vmcnt(15) lgkmcnt(1)
	v_pk_fma_f32 v[248:249], v[248:249], s[24:25], v[180:181] op_sel_hi:[1,0,1]
	v_pk_fma_f32 v[250:251], v[250:251], s[24:25], v[182:183] op_sel_hi:[1,0,1]
	v_pk_add_f32 v[248:249], v[248:249], v[176:177]
	v_pk_add_f32 v[250:251], v[250:251], v[178:179]
	v_cvt_pk_bf16_f32 v248, v248, v249
	v_cvt_pk_bf16_f32 v249, v250, v251
	global_store_dwordx2 v174, v[248:249], s[98:99]
	s_waitcnt vmcnt(15) lgkmcnt(0)
	v_pk_fma_f32 v[252:253], v[252:253], s[24:25], v[184:185] op_sel_hi:[1,0,1]
	v_pk_fma_f32 v[254:255], v[254:255], s[24:25], v[186:187] op_sel_hi:[1,0,1]
	v_pk_add_f32 v[252:253], v[252:253], v[176:177]
	v_pk_add_f32 v[254:255], v[254:255], v[178:179]
	v_cvt_pk_bf16_f32 v252, v252, v253
	v_cvt_pk_bf16_f32 v253, v254, v255
	global_store_dwordx2 v175, v[252:253], s[98:99]
	v_readfirstlane_b32 s0, v0
	s_and_b32 s1, s0, 0xffffff00
	s_cmpk_lg_i32 s1, 0x100
	s_barrier
	s_cbranch_scc1 .LBB0_298
	s_lshl_b32 s0, s0, 1
	s_and_b32 s1, s0, 0x80
	v_or_b32_e32 v140, s1, v148
	s_and_b32 s0, s0, 0x100
	v_mul_u32_u24_e32 v140, 0x210, v140
	v_add3_u32 v140, v143, s0, v140
	ds_write2_b32 v140, v126, v122 offset1:16
	ds_write2_b32 v140, v127, v123 offset0:132 offset1:148
	v_add_u32_e32 v122, 0x400, v140
	ds_write2_b32 v122, v128, v124 offset0:8 offset1:24
	ds_write2_b32 v122, v129, v125 offset0:140 offset1:156
	ds_write2_b32 v140, v118, v114 offset0:32 offset1:48
	ds_write2_b32 v140, v119, v115 offset0:164 offset1:180
	ds_write2_b32 v122, v120, v116 offset0:40 offset1:56
	ds_write2_b32 v122, v121, v117 offset0:172 offset1:188
	v_add_u32_e32 v114, 0x2000, v140
	ds_write2_b32 v114, v110, v106 offset0:64 offset1:80
	ds_write2_b32 v114, v111, v107 offset0:196 offset1:212
	v_add_u32_e32 v106, 0x2400, v140
	ds_write2_b32 v106, v112, v108 offset0:72 offset1:88
	ds_write2_b32 v106, v113, v109 offset0:204 offset1:220
	ds_write2_b32 v114, v102, v98 offset0:96 offset1:112
	ds_write2_b32 v114, v103, v99 offset0:228 offset1:244
	ds_write2_b32 v106, v104, v100 offset0:104 offset1:120
	ds_write2_b32 v106, v105, v101 offset0:236 offset1:252
	v_add_u32_e32 v98, 0x4000, v140
	ds_write2_b32 v98, v94, v90 offset0:128 offset1:144
	v_add_u32_e32 v90, 0x4400, v140
	ds_write2_b32 v90, v95, v91 offset0:4 offset1:20
	ds_write2_b32 v90, v96, v92 offset0:136 offset1:152
	v_add_u32_e32 v91, 0x4800, v140
	ds_write2_b32 v91, v97, v93 offset0:12 offset1:28
	ds_write2_b32 v98, v86, v82 offset0:160 offset1:176
	ds_write2_b32 v90, v87, v83 offset0:36 offset1:52
	ds_write2_b32 v90, v88, v84 offset0:168 offset1:184
	ds_write2_b32 v91, v89, v85 offset0:44 offset1:60
	v_add_u32_e32 v82, 0x6000, v140
	ds_write2_b32 v82, v78, v74 offset0:192 offset1:208
	v_add_u32_e32 v74, 0x6400, v140
	ds_write2_b32 v74, v79, v75 offset0:68 offset1:84
	ds_write2_b32 v74, v80, v76 offset0:200 offset1:216
	v_add_u32_e32 v75, 0x6800, v140
	ds_write2_b32 v75, v81, v77 offset0:76 offset1:92
; DI unsigned pack2(float a, float b) { const f32x2 v = {a, b}; const bf16x2_t r = __builtin_convertvector(v, bf16x2_t); return __builtin_bit_cast(unsigned, r); }
; template <int HF>
; DI void stage_acc_big(const f32x4 (&acc)[8][4], char* smem, const int g, const int r16) {
;   const int w = __builtin_amdgcn_readfirstlane(threadIdx.x >> 6), wm = w & 1, wn = w >> 1;
;   if ((wn >> 1) != HF) return;
;   float* ct = (float*)smem;
; #pragma unroll
;   for (int mi = 0; mi < 8; ++mi)
; #pragma unroll
;     for (int ni = 0; ni < 4; ++ni)
; #pragma unroll
;       for (int j = 0; j < 4; ++j) ct[(128 * wm + 16 * mi + 4 * g + j) * CT_PITCH + 64 * (wn & 1) + 16 * ni + r16] = acc[mi][ni][j];
; }
; DI void outproj_epilogue(const Params& p, const char* smem, const int m0, const int n0) {
;   u16* rbuf = (u16*)(p.ws + WS_PU);
;   const float* ct = (const float*)smem;
; #pragma unroll 4
;   for (int i = 0; i < 16; ++i) {
;     const int c = threadIdx.x + NT * i, row = c >> 5, ch = c & 31;
;     const float4 y = *(const float4*)(ct + row * CT_PITCH + 4 * ch);
;     const size_t o = (size_t)(m0 + row) * 1024 + n0 + 4 * ch;
;     const float4 xv = *(const float4*)(p.x + o), bv = *(const float4*)(p.b_out + n0 + 4 * ch);
;     uint2 r; r.x = pack2(ALPHA * xv.x + y.x + bv.x, ALPHA * xv.y + y.y + bv.y); r.y = pack2(ALPHA * xv.z + y.z + bv.z, ALPHA * xv.w + y.w + bv.w);
;     *(uint2*)(rbuf + o) = r;
;   }
	ds_write2_b32 v82, v66, v62 offset0:224 offset1:240
	ds_write2_b32 v74, v67, v63 offset0:100 offset1:116
	ds_write2_b32 v74, v68, v64 offset0:232 offset1:248
	ds_write2_b32 v75, v69, v65 offset0:108 offset1:124
	v_add_u32_e32 v62, 0x8400, v140
	ds_write2_b32 v62, v58, v54 offset1:16
	ds_write2_b32 v62, v59, v55 offset0:132 offset1:148
	v_add_u32_e32 v54, 0x8800, v140
	ds_write2_b32 v54, v60, v56 offset0:8 offset1:24
	ds_write2_b32 v54, v61, v57 offset0:140 offset1:156
	ds_write2_b32 v62, v50, v46 offset0:32 offset1:48
	ds_write2_b32 v62, v51, v47 offset0:164 offset1:180
	ds_write2_b32 v54, v52, v48 offset0:40 offset1:56
	ds_write2_b32 v54, v53, v49 offset0:172 offset1:188
	v_add_u32_e32 v46, 0xa400, v140
	ds_write2_b32 v46, v42, v38 offset0:64 offset1:80
	ds_write2_b32 v46, v43, v39 offset0:196 offset1:212
	v_add_u32_e32 v38, 0xa800, v140
	ds_write2_b32 v38, v44, v40 offset0:72 offset1:88
	ds_write2_b32 v38, v45, v41 offset0:204 offset1:220
	ds_write2_b32 v46, v34, v30 offset0:96 offset1:112
	ds_write2_b32 v46, v35, v31 offset0:228 offset1:244
	ds_write2_b32 v38, v36, v32 offset0:104 offset1:120
	ds_write2_b32 v38, v37, v33 offset0:236 offset1:252
	v_add_u32_e32 v30, 0xc400, v140
	ds_write2_b32 v30, v26, v22 offset0:128 offset1:144
	v_add_u32_e32 v22, 0xc800, v140
	ds_write2_b32 v22, v27, v23 offset0:4 offset1:20
	ds_write2_b32 v22, v28, v24 offset0:136 offset1:152
	v_add_u32_e32 v23, 0xcc00, v140
	ds_write2_b32 v23, v29, v25 offset0:12 offset1:28
	ds_write2_b32 v30, v18, v14 offset0:160 offset1:176
	ds_write2_b32 v22, v19, v15 offset0:36 offset1:52
	ds_write2_b32 v22, v20, v16 offset0:168 offset1:184
	ds_write2_b32 v23, v21, v17 offset0:44 offset1:60
	v_add_u32_e32 v14, 0xe400, v140
	ds_write2_b32 v14, v10, v6 offset0:192 offset1:208
	v_add_u32_e32 v6, 0xe800, v140
	ds_write2_b32 v6, v11, v7 offset0:68 offset1:84
	ds_write2_b32 v6, v12, v8 offset0:200 offset1:216
	v_add_u32_e32 v7, 0xec00, v140
	ds_write2_b32 v7, v13, v9 offset0:76 offset1:92
	ds_write2_b32 v14, v2, v70 offset0:224 offset1:240
	ds_write2_b32 v6, v3, v71 offset0:100 offset1:116
	ds_write2_b32 v6, v4, v72 offset0:232 offset1:248
	ds_write2_b32 v7, v5, v73 offset0:108 offset1:124
.LBB0_298:
	s_or_b32 s0, s26, 0x80
	s_ashr_i32 s1, s0, 31
	v_mov_b32_e32 v3, s1
	v_or_b32_e32 v2, s0, v130
	v_lshl_add_u64 v[4:5], s[26:27], 0, v[130:131]
	s_mov_b32 s0, 0
	v_mov_b32_e32 v6, v154
	v_mov_b32_e32 v7, v152
	v_mov_b32_e32 v8, v150
	v_lshl_add_u32 v180, v164, 10, v4
	v_lshl_add_u32 v181, v163, 10, v4
	v_lshl_add_u32 v183, v162, 10, v4
	v_add_u32_e32 v182, 0x8000, v180
	v_lshlrev_b32_e32 v168, 2, v180
	v_lshlrev_b32_e32 v169, 2, v181
	v_lshlrev_b32_e32 v170, 2, v182
	v_lshlrev_b32_e32 v171, 2, v183
	v_lshl_add_u32 v180, v164, 10, v2
	v_lshl_add_u32 v181, v163, 10, v2
	v_lshl_add_u32 v183, v162, 10, v2
	v_add_u32_e32 v182, 0x8000, v180
	v_lshlrev_b32_e32 v172, 1, v180
	v_lshlrev_b32_e32 v173, 1, v181
	v_lshlrev_b32_e32 v174, 1, v182
	v_lshlrev_b32_e32 v175, 1, v183
	global_load_dwordx4 v[176:179], v[138:139], off offset:512
	s_mov_b64 s[98:99], s[52:53]
	global_load_dwordx4 v[188:191], v168, s[98:99] offset:512
	global_load_dwordx4 v[192:195], v169, s[98:99] offset:512
	global_load_dwordx4 v[196:199], v170, s[98:99] offset:512
	global_load_dwordx4 v[202:205], v171, s[98:99] offset:512
	s_add_u32 s98, s98, 0x40000
	s_addc_u32 s99, s99, 0
	global_load_dwordx4 v[206:209], v168, s[98:99] offset:512
	global_load_dwordx4 v[210:213], v169, s[98:99] offset:512
	global_load_dwordx4 v[214:217], v170, s[98:99] offset:512
	global_load_dwordx4 v[218:221], v171, s[98:99] offset:512
	s_add_u32 s98, s98, 0x40000
	s_addc_u32 s99, s99, 0
	global_load_dwordx4 v[222:225], v168, s[98:99] offset:512
	global_load_dwordx4 v[226:229], v169, s[98:99] offset:512
	global_load_dwordx4 v[230:233], v170, s[98:99] offset:512
	global_load_dwordx4 v[234:237], v171, s[98:99] offset:512
	s_add_u32 s98, s98, 0x40000
	s_addc_u32 s99, s99, 0
	global_load_dwordx4 v[240:243], v168, s[98:99] offset:512
	global_load_dwordx4 v[244:247], v169, s[98:99] offset:512
	global_load_dwordx4 v[248:251], v170, s[98:99] offset:512
	global_load_dwordx4 v[252:255], v171, s[98:99] offset:512
	s_waitcnt lgkmcnt(0)
	s_barrier
	s_mov_b64 s[98:99], s[14:15]
	ds_read_b128 v[180:183], v6
	ds_read_b128 v[184:187], v7
	s_waitcnt vmcnt(15) lgkmcnt(1)
	v_pk_fma_f32 v[188:189], v[188:189], s[24:25], v[180:181] op_sel_hi:[1,0,1]
	v_pk_fma_f32 v[190:191], v[190:191], s[24:25], v[182:183] op_sel_hi:[1,0,1]
	ds_read_b128 v[180:183], v6 offset:16896
	v_pk_add_f32 v[188:189], v[188:189], v[176:177]
	v_pk_add_f32 v[190:191], v[190:191], v[178:179]
	v_cvt_pk_bf16_f32 v188, v188, v189
	v_cvt_pk_bf16_f32 v189, v190, v191
	global_store_dwordx2 v172, v[188:189], s[98:99]
	s_waitcnt vmcnt(15) lgkmcnt(1)
	v_pk_fma_f32 v[192:193], v[192:193], s[24:25], v[184:185] op_sel_hi:[1,0,1]
	v_pk_fma_f32 v[194:195], v[194:195], s[24:25], v[186:187] op_sel_hi:[1,0,1]
	ds_read_b128 v[184:187], v8
	v_pk_add_f32 v[192:193], v[192:193], v[176:177]
	v_pk_add_f32 v[194:195], v[194:195], v[178:179]
	v_cvt_pk_bf16_f32 v192, v192, v193
	v_cvt_pk_bf16_f32 v193, v194, v195
	global_store_dwordx2 v173, v[192:193], s[98:99]
	s_waitcnt vmcnt(15) lgkmcnt(1)
	v_pk_fma_f32 v[196:197], v[196:197], s[24:25], v[180:181] op_sel_hi:[1,0,1]
	v_pk_fma_f32 v[198:199], v[198:199], s[24:25], v[182:183] op_sel_hi:[1,0,1]
	v_pk_add_f32 v[196:197], v[196:197], v[176:177]
	v_pk_add_f32 v[198:199], v[198:199], v[178:179]
	v_cvt_pk_bf16_f32 v196, v196, v197
	v_cvt_pk_bf16_f32 v197, v198, v199
	global_store_dwordx2 v174, v[196:197], s[98:99]
	s_waitcnt vmcnt(15) lgkmcnt(0)
; DI unsigned pack2(float a, float b) { const f32x2 v = {a, b}; const bf16x2_t r = __builtin_convertvector(v, bf16x2_t); return __builtin_bit_cast(unsigned, r); }
; DI void outproj_epilogue(const Params& p, const char* smem, const int m0, const int n0) {
;   u16* rbuf = (u16*)(p.ws + WS_PU);
;   const float* ct = (const float*)smem;
; #pragma unroll 4
;   for (int i = 0; i < 16; ++i) {
;     const int c = threadIdx.x + NT * i, row = c >> 5, ch = c & 31;
;     const float4 y = *(const float4*)(ct + row * CT_PITCH + 4 * ch);
;     const size_t o = (size_t)(m0 + row) * 1024 + n0 + 4 * ch;
;     const float4 xv = *(const float4*)(p.x + o), bv = *(const float4*)(p.b_out + n0 + 4 * ch);
;     uint2 r; r.x = pack2(ALPHA * xv.x + y.x + bv.x, ALPHA * xv.y + y.y + bv.y); r.y = pack2(ALPHA * xv.z + y.z + bv.z, ALPHA * xv.w + y.w + bv.w);
;     *(uint2*)(rbuf + o) = r;
;   }
; }
	v_pk_fma_f32 v[202:203], v[202:203], s[24:25], v[184:185] op_sel_hi:[1,0,1]
	v_pk_fma_f32 v[204:205], v[204:205], s[24:25], v[186:187] op_sel_hi:[1,0,1]
	v_pk_add_f32 v[202:203], v[202:203], v[176:177]
	v_pk_add_f32 v[204:205], v[204:205], v[178:179]
	v_cvt_pk_bf16_f32 v202, v202, v203
	v_cvt_pk_bf16_f32 v203, v204, v205
	global_store_dwordx2 v175, v[202:203], s[98:99]
	v_add_u32_e32 v6, 0x8400, v6
	v_add_u32_e32 v7, 0x8400, v7
	v_add_u32_e32 v8, 0x8400, v8
	s_add_u32 s98, s98, 0x20000
	s_addc_u32 s99, s99, 0
	ds_read_b128 v[180:183], v6
	ds_read_b128 v[184:187], v7
	s_waitcnt vmcnt(15) lgkmcnt(1)
	v_pk_fma_f32 v[206:207], v[206:207], s[24:25], v[180:181] op_sel_hi:[1,0,1]
	v_pk_fma_f32 v[208:209], v[208:209], s[24:25], v[182:183] op_sel_hi:[1,0,1]
	ds_read_b128 v[180:183], v6 offset:16896
	v_pk_add_f32 v[206:207], v[206:207], v[176:177]
	v_pk_add_f32 v[208:209], v[208:209], v[178:179]
	v_cvt_pk_bf16_f32 v206, v206, v207
	v_cvt_pk_bf16_f32 v207, v208, v209
	global_store_dwordx2 v172, v[206:207], s[98:99]
	s_waitcnt vmcnt(15) lgkmcnt(1)
	v_pk_fma_f32 v[210:211], v[210:211], s[24:25], v[184:185] op_sel_hi:[1,0,1]
	v_pk_fma_f32 v[212:213], v[212:213], s[24:25], v[186:187] op_sel_hi:[1,0,1]
	ds_read_b128 v[184:187], v8
	v_pk_add_f32 v[210:211], v[210:211], v[176:177]
	v_pk_add_f32 v[212:213], v[212:213], v[178:179]
	v_cvt_pk_bf16_f32 v210, v210, v211
	v_cvt_pk_bf16_f32 v211, v212, v213
	global_store_dwordx2 v173, v[210:211], s[98:99]
	s_waitcnt vmcnt(15) lgkmcnt(1)
	v_pk_fma_f32 v[214:215], v[214:215], s[24:25], v[180:181] op_sel_hi:[1,0,1]
	v_pk_fma_f32 v[216:217], v[216:217], s[24:25], v[182:183] op_sel_hi:[1,0,1]
	v_pk_add_f32 v[214:215], v[214:215], v[176:177]
	v_pk_add_f32 v[216:217], v[216:217], v[178:179]
	v_cvt_pk_bf16_f32 v214, v214, v215
	v_cvt_pk_bf16_f32 v215, v216, v217
	global_store_dwordx2 v174, v[214:215], s[98:99]
	s_waitcnt vmcnt(15) lgkmcnt(0)
	v_pk_fma_f32 v[218:219], v[218:219], s[24:25], v[184:185] op_sel_hi:[1,0,1]
	v_pk_fma_f32 v[220:221], v[220:221], s[24:25], v[186:187] op_sel_hi:[1,0,1]
	v_pk_add_f32 v[218:219], v[218:219], v[176:177]
	v_pk_add_f32 v[220:221], v[220:221], v[178:179]
	v_cvt_pk_bf16_f32 v218, v218, v219
	v_cvt_pk_bf16_f32 v219, v220, v221
	global_store_dwordx2 v175, v[218:219], s[98:99]
	v_add_u32_e32 v6, 0x8400, v6
	v_add_u32_e32 v7, 0x8400, v7
	v_add_u32_e32 v8, 0x8400, v8
	s_add_u32 s98, s98, 0x20000
	s_addc_u32 s99, s99, 0
	ds_read_b128 v[180:183], v6
	ds_read_b128 v[184:187], v7
	s_waitcnt vmcnt(15) lgkmcnt(1)
	v_pk_fma_f32 v[222:223], v[222:223], s[24:25], v[180:181] op_sel_hi:[1,0,1]
	v_pk_fma_f32 v[224:225], v[224:225], s[24:25], v[182:183] op_sel_hi:[1,0,1]
	ds_read_b128 v[180:183], v6 offset:16896
	v_pk_add_f32 v[222:223], v[222:223], v[176:177]
	v_pk_add_f32 v[224:225], v[224:225], v[178:179]
	v_cvt_pk_bf16_f32 v222, v222, v223
	v_cvt_pk_bf16_f32 v223, v224, v225
	global_store_dwordx2 v172, v[222:223], s[98:99]
	s_waitcnt vmcnt(15) lgkmcnt(1)
	v_pk_fma_f32 v[226:227], v[226:227], s[24:25], v[184:185] op_sel_hi:[1,0,1]
	v_pk_fma_f32 v[228:229], v[228:229], s[24:25], v[186:187] op_sel_hi:[1,0,1]
	ds_read_b128 v[184:187], v8
	v_pk_add_f32 v[226:227], v[226:227], v[176:177]
	v_pk_add_f32 v[228:229], v[228:229], v[178:179]
	v_cvt_pk_bf16_f32 v226, v226, v227
	v_cvt_pk_bf16_f32 v227, v228, v229
	global_store_dwordx2 v173, v[226:227], s[98:99]
	s_waitcnt vmcnt(15) lgkmcnt(1)
	v_pk_fma_f32 v[230:231], v[230:231], s[24:25], v[180:181] op_sel_hi:[1,0,1]
	v_pk_fma_f32 v[232:233], v[232:233], s[24:25], v[182:183] op_sel_hi:[1,0,1]
	v_pk_add_f32 v[230:231], v[230:231], v[176:177]
	v_pk_add_f32 v[232:233], v[232:233], v[178:179]
	v_cvt_pk_bf16_f32 v230, v230, v231
	v_cvt_pk_bf16_f32 v231, v232, v233
	global_store_dwordx2 v174, v[230:231], s[98:99]
	s_waitcnt vmcnt(15) lgkmcnt(0)
	v_pk_fma_f32 v[234:235], v[234:235], s[24:25], v[184:185] op_sel_hi:[1,0,1]
	v_pk_fma_f32 v[236:237], v[236:237], s[24:25], v[186:187] op_sel_hi:[1,0,1]
	v_pk_add_f32 v[234:235], v[234:235], v[176:177]
	v_pk_add_f32 v[236:237], v[236:237], v[178:179]
	v_cvt_pk_bf16_f32 v234, v234, v235
	v_cvt_pk_bf16_f32 v235, v236, v237
	global_store_dwordx2 v175, v[234:235], s[98:99]
	v_add_u32_e32 v6, 0x8400, v6
	v_add_u32_e32 v7, 0x8400, v7
	v_add_u32_e32 v8, 0x8400, v8
	s_add_u32 s98, s98, 0x20000
	s_addc_u32 s99, s99, 0
	ds_read_b128 v[180:183], v6
	ds_read_b128 v[184:187], v7
	s_waitcnt vmcnt(15) lgkmcnt(1)
	v_pk_fma_f32 v[240:241], v[240:241], s[24:25], v[180:181] op_sel_hi:[1,0,1]
	v_pk_fma_f32 v[242:243], v[242:243], s[24:25], v[182:183] op_sel_hi:[1,0,1]
	ds_read_b128 v[180:183], v6 offset:16896
	v_pk_add_f32 v[240:241], v[240:241], v[176:177]
	v_pk_add_f32 v[242:243], v[242:243], v[178:179]
	v_cvt_pk_bf16_f32 v240, v240, v241
	v_cvt_pk_bf16_f32 v241, v242, v243
	global_store_dwordx2 v172, v[240:241], s[98:99]
	s_waitcnt vmcnt(15) lgkmcnt(1)
	v_pk_fma_f32 v[244:245], v[244:245], s[24:25], v[184:185] op_sel_hi:[1,0,1]
	v_pk_fma_f32 v[246:247], v[246:247], s[24:25], v[186:187] op_sel_hi:[1,0,1]
	ds_read_b128 v[184:187], v8
	v_pk_add_f32 v[244:245], v[244:245], v[176:177]
	v_pk_add_f32 v[246:247], v[246:247], v[178:179]
	v_cvt_pk_bf16_f32 v244, v244, v245
	v_cvt_pk_bf16_f32 v245, v246, v247
	global_store_dwordx2 v173, v[244:245], s[98:99]
	s_waitcnt vmcnt(15) lgkmcnt(1)
	v_pk_fma_f32 v[248:249], v[248:249], s[24:25], v[180:181] op_sel_hi:[1,0,1]
	v_pk_fma_f32 v[250:251], v[250:251], s[24:25], v[182:183] op_sel_hi:[1,0,1]
	v_pk_add_f32 v[248:249], v[248:249], v[176:177]
	v_pk_add_f32 v[250:251], v[250:251], v[178:179]
	v_cvt_pk_bf16_f32 v248, v248, v249
	v_cvt_pk_bf16_f32 v249, v250, v251
	global_store_dwordx2 v174, v[248:249], s[98:99]
	s_waitcnt vmcnt(15) lgkmcnt(0)
	v_pk_fma_f32 v[252:253], v[252:253], s[24:25], v[184:185] op_sel_hi:[1,0,1]
	v_pk_fma_f32 v[254:255], v[254:255], s[24:25], v[186:187] op_sel_hi:[1,0,1]
	v_pk_add_f32 v[252:253], v[252:253], v[176:177]
	v_pk_add_f32 v[254:255], v[254:255], v[178:179]
	v_cvt_pk_bf16_f32 v252, v252, v253
	v_cvt_pk_bf16_f32 v253, v254, v255
	global_store_dwordx2 v175, v[252:253], s[98:99]
	s_add_i32 s31, s31, s3
	s_add_i32 s34, s34, 1
	s_cmpk_lt_i32 s31, 0x200
	s_barrier
	s_cbranch_scc1 .LBB0_286
	s_branch .LBB0_303

; __global__ void __launch_bounds__(NT) hymba_fwd(Params p) {
	.amdhsa_kernel _Z9hymba_fwd6Params
		.amdhsa_group_segment_fixed_size 0
		.amdhsa_private_segment_fixed_size 0
		.amdhsa_kernarg_size 416
		.amdhsa_user_sgpr_count 2
		.amdhsa_user_sgpr_dispatch_ptr 0
		.amdhsa_user_sgpr_queue_ptr 0
		.amdhsa_user_sgpr_kernarg_segment_ptr 1
		.amdhsa_user_sgpr_dispatch_id 0
		.amdhsa_user_sgpr_kernarg_preload_length 0
		.amdhsa_user_sgpr_kernarg_preload_offset 0
		.amdhsa_user_sgpr_private_segment_size 0
		.amdhsa_uses_dynamic_stack 0
		.amdhsa_enable_private_segment 0
		.amdhsa_system_sgpr_workgroup_id_x 1
		.amdhsa_system_sgpr_workgroup_id_y 0
		.amdhsa_system_sgpr_workgroup_id_z 0
		.amdhsa_system_sgpr_workgroup_info 0
		.amdhsa_system_vgpr_workitem_id 0
		.amdhsa_next_free_vgpr 256
		.amdhsa_next_free_sgpr 100
		.amdhsa_accum_offset 256
		.amdhsa_reserve_vcc 1
		.amdhsa_float_round_mode_32 0
		.amdhsa_float_round_mode_16_64 0
		.amdhsa_float_denorm_mode_32 3
		.amdhsa_float_denorm_mode_16_64 3
		.amdhsa_dx10_clamp 1
		.amdhsa_ieee_mode 1
		.amdhsa_fp16_overflow 0
		.amdhsa_tg_split 0
		.amdhsa_exception_fp_ieee_invalid_op 0
		.amdhsa_exception_fp_denorm_src 0
		.amdhsa_exception_fp_ieee_div_zero 0
		.amdhsa_exception_fp_ieee_overflow 0
		.amdhsa_exception_fp_ieee_underflow 0
		.amdhsa_exception_fp_ieee_inexact 0
		.amdhsa_exception_int_div_zero 0
	.end_amdhsa_kernel

; __global__ void __launch_bounds__(NT) hymba_fwd(Params p) {
amdhsa.kernels:
  - .agpr_count:     0
    .args:
      - .offset:         0
        .size:           160
        .value_kind:     by_value
      - .offset:         160
        .size:           4
        .value_kind:     hidden_block_count_x
      - .offset:         164
        .size:           4
        .value_kind:     hidden_block_count_y
      - .offset:         168
        .size:           4
        .value_kind:     hidden_block_count_z
      - .offset:         172
        .size:           2
        .value_kind:     hidden_group_size_x
      - .offset:         174
        .size:           2
        .value_kind:     hidden_group_size_y
      - .offset:         176
        .size:           2
        .value_kind:     hidden_group_size_z
      - .offset:         178
        .size:           2
        .value_kind:     hidden_remainder_x
      - .offset:         180
        .size:           2
        .value_kind:     hidden_remainder_y
      - .offset:         182
        .size:           2
        .value_kind:     hidden_remainder_z
      - .offset:         200
        .size:           8
        .value_kind:     hidden_global_offset_x
      - .offset:         208
        .size:           8
        .value_kind:     hidden_global_offset_y
      - .offset:         216
        .size:           8
        .value_kind:     hidden_global_offset_z
      - .offset:         224
        .size:           2
        .value_kind:     hidden_grid_dims
      - .offset:         280
        .size:           4
        .value_kind:     hidden_dynamic_lds_size
    .group_segment_fixed_size: 0
    .kernarg_segment_align: 8
    .kernarg_segment_size: 416
    .language:       OpenCL C
    .language_version:
      - 2
      - 0
    .max_flat_workgroup_size: 512
    .name:           _Z9hymba_fwd6Params
    .private_segment_fixed_size: 0
    .sgpr_count:     106
    .sgpr_spill_count: 26
    .symbol:         _Z9hymba_fwd6Params.kd
    .uniform_work_group_size: 1
    .uses_dynamic_stack: false
    .vgpr_count:     256
    .vgpr_spill_count: 0
    .wavefront_size: 64
